# adds: epilogue-entry vmcnt(0) relaxed to vmcnt(8) in the Swiglu/Store GEMM variants (only the last 8 LDS-DMA loads can be outstanding there)
# speedup vs baseline: 1.0099x; 1.0025x over previous
; __device__ __forceinline__ unsigned cvtpk(float lo, float hi) { f32x2_t v = {lo, hi}; bf16x2_t b = __builtin_convertvector(v, bf16x2_t); return __builtin_bit_cast(unsigned, b); }
;     __device__ __forceinline__ void operator()(const f32x4 (&acc)[2][2][4][2], const Unit& u, int wr, int wc, int fr, int fq, const float (&pre)[8]) const {
;     ...
;             for (int m = 0; m < 4; ++m) { bf16_t* rowp = O + (size_t)(row0 + ai * 128 + m * 16) * ldc + col0; const float r = rsqrtf(pre[ai * 4 + m] * (1.f / 1024.f) + 1e-6f);
;                 const float k1 = r * -1.4426950408889634f, rr = r * r; u32x4 w;
; #pragma unroll
;                 for (int n = 0; n < 2; ++n) { const f32x4 g = acc[ai][0][m][n], uu = acc[ai][1][m][n]; const f32x4 t = g * uu, x = g * k1; f32x4 d;
;                     d[0] = __builtin_amdgcn_exp2f(x[0]); d[1] = __builtin_amdgcn_exp2f(x[1]); d[2] = __builtin_amdgcn_exp2f(x[2]); d[3] = __builtin_amdgcn_exp2f(x[3]);
;                     d = d + 1.0f;
;                     d[0] = __builtin_amdgcn_rcpf(d[0]); d[1] = __builtin_amdgcn_rcpf(d[1]); d[2] = __builtin_amdgcn_rcpf(d[2]); d[3] = __builtin_amdgcn_rcpf(d[3]);
;                     const f32x4 o = (t * d) * rr;
;                     if (n == 0) { w.x = cvtpk(o[0], o[1]); w.y = cvtpk(o[2], o[3]); } else { w.z = cvtpk(o[0], o[1]); w.w = cvtpk(o[2], o[3]); } }
;                 *(u32x4*)rowp = w; }
.LBB0_183:
	s_waitcnt vmcnt(8)
	v_fmamk_f32 v153, v153, 0x3a800000, v189
	v_cmp_gt_f32_e32 vcc, s27, v153
	v_mul_f32_e32 v155, 0x4b800000, v153
	v_pk_mul_f32 v[124:125], v[128:129], v[124:125]
	v_cndmask_b32_e32 v153, v153, v155, vcc
	v_rsq_f32_e32 v153, v153
	v_pk_mul_f32 v[122:123], v[126:127], v[122:123]
	v_pk_mul_f32 v[116:117], v[120:121], v[116:117]
	v_pk_mul_f32 v[114:115], v[118:119], v[114:115]
	v_mul_f32_e32 v155, 0x45800000, v153
	v_cndmask_b32_e32 v153, v153, v155, vcc
	v_mul_f32_e32 v156, 0xbfb8aa3b, v153
	v_pk_mul_f32 v[128:129], v[156:157], v[128:129] op_sel_hi:[0,1]
	v_pk_mul_f32 v[126:127], v[156:157], v[126:127] op_sel_hi:[0,1]
	v_pk_mul_f32 v[120:121], v[156:157], v[120:121] op_sel_hi:[0,1]
	v_pk_mul_f32 v[118:119], v[156:157], v[118:119] op_sel_hi:[0,1]
	v_exp_f32_e32 v126, v126
	v_exp_f32_e32 v127, v127
	v_exp_f32_e32 v128, v128
	v_exp_f32_e32 v129, v129
	v_exp_f32_e32 v118, v118
	v_exp_f32_e32 v119, v119
	v_exp_f32_e32 v120, v120
	v_exp_f32_e32 v121, v121
	v_pk_add_f32 v[128:129], v[128:129], 1.0 op_sel_hi:[1,0]
	v_pk_add_f32 v[126:127], v[126:127], 1.0 op_sel_hi:[1,0]
	v_pk_add_f32 v[118:119], v[118:119], 1.0 op_sel_hi:[1,0]
	v_pk_add_f32 v[120:121], v[120:121], 1.0 op_sel_hi:[1,0]
	v_rcp_f32_e32 v126, v126
	v_rcp_f32_e32 v127, v127
	v_rcp_f32_e32 v128, v128
	v_rcp_f32_e32 v129, v129
	v_rcp_f32_e32 v118, v118
	v_rcp_f32_e32 v119, v119
	v_rcp_f32_e32 v120, v120
	v_rcp_f32_e32 v121, v121
	v_lshl_or_b32 v140, s24, 7, v145
	v_readlane_b32 s14, v252, 20
	v_ashrrev_i32_e32 v141, 31, v140
	v_readlane_b32 s15, v252, 21
	v_mul_f32_e32 v158, v153, v153
	v_pk_mul_f32 v[122:123], v[126:127], v[122:123]
	v_pk_mul_f32 v[124:125], v[128:129], v[124:125]
	v_pk_mul_f32 v[114:115], v[118:119], v[114:115]
	v_pk_mul_f32 v[116:117], v[120:121], v[116:117]
	v_lshl_add_u32 v154, s3, 8, v142
	v_lshl_add_u64 v[140:141], v[140:141], 1, s[14:15]
	v_pk_mul_f32 v[124:125], v[158:159], v[124:125] op_sel_hi:[0,1]
	v_pk_mul_f32 v[122:123], v[158:159], v[122:123] op_sel_hi:[0,1]
	v_pk_mul_f32 v[116:117], v[158:159], v[116:117] op_sel_hi:[0,1]
	v_pk_mul_f32 v[114:115], v[158:159], v[114:115] op_sel_hi:[0,1]
	v_cvt_pk_bf16_f32 v122, v122, v123
	v_cvt_pk_bf16_f32 v123, v124, v125
	v_cvt_pk_bf16_f32 v124, v114, v115
	v_cvt_pk_bf16_f32 v125, v116, v117
	v_mad_i64_i32 v[114:115], s[14:15], v154, s45, v[140:141]
	global_store_dwordx4 v[114:115], v[122:125], off
	v_fmamk_f32 v114, v152, 0x3a800000, v189
	v_cmp_gt_f32_e32 vcc, s27, v114
	v_mul_f32_e32 v116, 0x4b800000, v114
	v_or_b32_e32 v115, 16, v154
	v_cndmask_b32_e32 v114, v114, v116, vcc
	v_rsq_f32_e32 v114, v114
	v_pk_mul_f32 v[108:109], v[112:113], v[108:109]
	v_pk_mul_f32 v[106:107], v[110:111], v[106:107]
	v_pk_mul_f32 v[100:101], v[104:105], v[100:101]
	v_mul_f32_e32 v116, 0x45800000, v114
	v_cndmask_b32_e32 v116, v114, v116, vcc
	v_mul_f32_e32 v114, 0xbfb8aa3b, v116
	v_pk_mul_f32 v[112:113], v[114:115], v[112:113] op_sel_hi:[0,1]
	v_pk_mul_f32 v[110:111], v[114:115], v[110:111] op_sel_hi:[0,1]
	v_pk_mul_f32 v[98:99], v[102:103], v[98:99]
	v_pk_mul_f32 v[104:105], v[114:115], v[104:105] op_sel_hi:[0,1]
	v_pk_mul_f32 v[102:103], v[114:115], v[102:103] op_sel_hi:[0,1]
	v_exp_f32_e32 v110, v110
	v_exp_f32_e32 v111, v111
	v_exp_f32_e32 v112, v112
	v_exp_f32_e32 v113, v113
	v_exp_f32_e32 v102, v102
	v_exp_f32_e32 v103, v103
	v_exp_f32_e32 v104, v104
	v_exp_f32_e32 v105, v105
	v_pk_add_f32 v[112:113], v[112:113], 1.0 op_sel_hi:[1,0]
	v_pk_add_f32 v[110:111], v[110:111], 1.0 op_sel_hi:[1,0]
	v_pk_add_f32 v[102:103], v[102:103], 1.0 op_sel_hi:[1,0]
	v_pk_add_f32 v[104:105], v[104:105], 1.0 op_sel_hi:[1,0]
	v_rcp_f32_e32 v110, v110
	v_rcp_f32_e32 v111, v111
	v_rcp_f32_e32 v112, v112
	v_rcp_f32_e32 v113, v113
	v_rcp_f32_e32 v102, v102
	v_rcp_f32_e32 v103, v103
	v_rcp_f32_e32 v104, v104
	v_rcp_f32_e32 v105, v105
	v_mul_f32_e32 v116, v116, v116
	v_pk_mul_f32 v[106:107], v[110:111], v[106:107]
	v_pk_mul_f32 v[108:109], v[112:113], v[108:109]
	v_pk_mul_f32 v[98:99], v[102:103], v[98:99]
	v_pk_mul_f32 v[100:101], v[104:105], v[100:101]
	v_pk_mul_f32 v[108:109], v[116:117], v[108:109] op_sel_hi:[0,1]
	v_pk_mul_f32 v[106:107], v[116:117], v[106:107] op_sel_hi:[0,1]
	v_pk_mul_f32 v[100:101], v[116:117], v[100:101] op_sel_hi:[0,1]
	v_pk_mul_f32 v[98:99], v[116:117], v[98:99] op_sel_hi:[0,1]
	v_cvt_pk_bf16_f32 v106, v106, v107
	v_cvt_pk_bf16_f32 v107, v108, v109
	v_cvt_pk_bf16_f32 v108, v98, v99
	v_cvt_pk_bf16_f32 v109, v100, v101
	v_mad_i64_i32 v[98:99], s[14:15], v115, s45, v[140:141]
	global_store_dwordx4 v[98:99], v[106:109], off
	v_fmamk_f32 v98, v151, 0x3a800000, v189
	v_cmp_gt_f32_e32 vcc, s27, v98
	v_mul_f32_e32 v100, 0x4b800000, v98
	v_or_b32_e32 v99, 32, v154
	v_cndmask_b32_e32 v98, v98, v100, vcc
	v_rsq_f32_e32 v98, v98
	v_pk_mul_f32 v[92:93], v[96:97], v[92:93]
	v_pk_mul_f32 v[90:91], v[94:95], v[90:91]
	v_pk_mul_f32 v[84:85], v[88:89], v[84:85]
	v_mul_f32_e32 v100, 0x45800000, v98
	v_cndmask_b32_e32 v100, v98, v100, vcc
	v_mul_f32_e32 v98, 0xbfb8aa3b, v100
	v_pk_mul_f32 v[96:97], v[98:99], v[96:97] op_sel_hi:[0,1]
	v_pk_mul_f32 v[94:95], v[98:99], v[94:95] op_sel_hi:[0,1]
	v_pk_mul_f32 v[82:83], v[86:87], v[82:83]
	v_pk_mul_f32 v[88:89], v[98:99], v[88:89] op_sel_hi:[0,1]
	v_pk_mul_f32 v[86:87], v[98:99], v[86:87] op_sel_hi:[0,1]
	v_exp_f32_e32 v94, v94
	v_exp_f32_e32 v95, v95
	v_exp_f32_e32 v96, v96
	v_exp_f32_e32 v97, v97
	v_exp_f32_e32 v86, v86
	v_exp_f32_e32 v87, v87
	v_exp_f32_e32 v88, v88
	v_exp_f32_e32 v89, v89
	v_pk_add_f32 v[96:97], v[96:97], 1.0 op_sel_hi:[1,0]
	v_pk_add_f32 v[94:95], v[94:95], 1.0 op_sel_hi:[1,0]
	v_pk_add_f32 v[86:87], v[86:87], 1.0 op_sel_hi:[1,0]
; __device__ __forceinline__ unsigned cvtpk(float lo, float hi) { f32x2_t v = {lo, hi}; bf16x2_t b = __builtin_convertvector(v, bf16x2_t); return __builtin_bit_cast(unsigned, b); }
;     __device__ __forceinline__ void operator()(const f32x4 (&acc)[2][2][4][2], const Unit& u, int wr, int wc, int fr, int fq, const float (&pre)[8]) const {
;     ...
;             for (int m = 0; m < 4; ++m) { bf16_t* rowp = O + (size_t)(row0 + ai * 128 + m * 16) * ldc + col0; const float r = rsqrtf(pre[ai * 4 + m] * (1.f / 1024.f) + 1e-6f);
;                 const float k1 = r * -1.4426950408889634f, rr = r * r; u32x4 w;
; #pragma unroll
;                 for (int n = 0; n < 2; ++n) { const f32x4 g = acc[ai][0][m][n], uu = acc[ai][1][m][n]; const f32x4 t = g * uu, x = g * k1; f32x4 d;
;                     d[0] = __builtin_amdgcn_exp2f(x[0]); d[1] = __builtin_amdgcn_exp2f(x[1]); d[2] = __builtin_amdgcn_exp2f(x[2]); d[3] = __builtin_amdgcn_exp2f(x[3]);
;                     d = d + 1.0f;
;                     d[0] = __builtin_amdgcn_rcpf(d[0]); d[1] = __builtin_amdgcn_rcpf(d[1]); d[2] = __builtin_amdgcn_rcpf(d[2]); d[3] = __builtin_amdgcn_rcpf(d[3]);
;                     const f32x4 o = (t * d) * rr;
;                     if (n == 0) { w.x = cvtpk(o[0], o[1]); w.y = cvtpk(o[2], o[3]); } else { w.z = cvtpk(o[0], o[1]); w.w = cvtpk(o[2], o[3]); } }
;                 *(u32x4*)rowp = w; }
	v_pk_add_f32 v[88:89], v[88:89], 1.0 op_sel_hi:[1,0]
	v_rcp_f32_e32 v94, v94
	v_rcp_f32_e32 v95, v95
	v_rcp_f32_e32 v96, v96
	v_rcp_f32_e32 v97, v97
	v_rcp_f32_e32 v86, v86
	v_rcp_f32_e32 v87, v87
	v_rcp_f32_e32 v88, v88
	v_rcp_f32_e32 v89, v89
	v_mul_f32_e32 v100, v100, v100
	v_pk_mul_f32 v[90:91], v[94:95], v[90:91]
	v_pk_mul_f32 v[92:93], v[96:97], v[92:93]
	v_pk_mul_f32 v[82:83], v[86:87], v[82:83]
	v_pk_mul_f32 v[84:85], v[88:89], v[84:85]
	v_pk_mul_f32 v[92:93], v[100:101], v[92:93] op_sel_hi:[0,1]
	v_pk_mul_f32 v[90:91], v[100:101], v[90:91] op_sel_hi:[0,1]
	v_pk_mul_f32 v[84:85], v[100:101], v[84:85] op_sel_hi:[0,1]
	v_pk_mul_f32 v[82:83], v[100:101], v[82:83] op_sel_hi:[0,1]
	v_cvt_pk_bf16_f32 v90, v90, v91
	v_cvt_pk_bf16_f32 v91, v92, v93
	v_cvt_pk_bf16_f32 v92, v82, v83
	v_cvt_pk_bf16_f32 v93, v84, v85
	v_mad_i64_i32 v[82:83], s[14:15], v99, s45, v[140:141]
	global_store_dwordx4 v[82:83], v[90:93], off
	v_fmamk_f32 v82, v150, 0x3a800000, v189
	v_cmp_gt_f32_e32 vcc, s27, v82
	v_mul_f32_e32 v84, 0x4b800000, v82
	v_or_b32_e32 v83, 48, v154
	v_cndmask_b32_e32 v82, v82, v84, vcc
	v_rsq_f32_e32 v82, v82
	v_pk_mul_f32 v[76:77], v[80:81], v[76:77]
	v_pk_mul_f32 v[74:75], v[78:79], v[74:75]
	v_pk_mul_f32 v[68:69], v[72:73], v[68:69]
	v_mul_f32_e32 v84, 0x45800000, v82
	v_cndmask_b32_e32 v84, v82, v84, vcc
	v_mul_f32_e32 v82, 0xbfb8aa3b, v84
	v_pk_mul_f32 v[80:81], v[82:83], v[80:81] op_sel_hi:[0,1]
	v_pk_mul_f32 v[78:79], v[82:83], v[78:79] op_sel_hi:[0,1]
	v_pk_mul_f32 v[66:67], v[70:71], v[66:67]
	v_pk_mul_f32 v[72:73], v[82:83], v[72:73] op_sel_hi:[0,1]
	v_pk_mul_f32 v[70:71], v[82:83], v[70:71] op_sel_hi:[0,1]
	v_exp_f32_e32 v78, v78
	v_exp_f32_e32 v79, v79
	v_exp_f32_e32 v80, v80
	v_exp_f32_e32 v81, v81
	v_exp_f32_e32 v70, v70
	v_exp_f32_e32 v71, v71
	v_exp_f32_e32 v72, v72
	v_exp_f32_e32 v73, v73
	v_pk_add_f32 v[80:81], v[80:81], 1.0 op_sel_hi:[1,0]
	v_pk_add_f32 v[78:79], v[78:79], 1.0 op_sel_hi:[1,0]
	v_pk_add_f32 v[70:71], v[70:71], 1.0 op_sel_hi:[1,0]
	v_pk_add_f32 v[72:73], v[72:73], 1.0 op_sel_hi:[1,0]
	v_rcp_f32_e32 v78, v78
	v_rcp_f32_e32 v79, v79
	v_rcp_f32_e32 v80, v80
	v_rcp_f32_e32 v81, v81
	v_rcp_f32_e32 v70, v70
	v_rcp_f32_e32 v71, v71
	v_rcp_f32_e32 v72, v72
	v_rcp_f32_e32 v73, v73
	v_mul_f32_e32 v84, v84, v84
	v_pk_mul_f32 v[74:75], v[78:79], v[74:75]
	v_pk_mul_f32 v[76:77], v[80:81], v[76:77]
	v_pk_mul_f32 v[66:67], v[70:71], v[66:67]
	v_pk_mul_f32 v[68:69], v[72:73], v[68:69]
	v_pk_mul_f32 v[76:77], v[84:85], v[76:77] op_sel_hi:[0,1]
	v_pk_mul_f32 v[74:75], v[84:85], v[74:75] op_sel_hi:[0,1]
	v_pk_mul_f32 v[68:69], v[84:85], v[68:69] op_sel_hi:[0,1]
	v_pk_mul_f32 v[66:67], v[84:85], v[66:67] op_sel_hi:[0,1]
	v_cvt_pk_bf16_f32 v74, v74, v75
	v_cvt_pk_bf16_f32 v75, v76, v77
	v_cvt_pk_bf16_f32 v76, v66, v67
	v_cvt_pk_bf16_f32 v77, v68, v69
	v_mad_i64_i32 v[66:67], s[14:15], v83, s45, v[140:141]
	global_store_dwordx4 v[66:67], v[74:77], off
	v_fmamk_f32 v66, v149, 0x3a800000, v189
	v_cmp_gt_f32_e32 vcc, s27, v66
	v_mul_f32_e32 v68, 0x4b800000, v66
	v_add_u32_e32 v67, 0x80, v154
	v_cndmask_b32_e32 v66, v66, v68, vcc
	v_rsq_f32_e32 v66, v66
	v_pk_mul_f32 v[60:61], v[64:65], v[60:61]
	v_pk_mul_f32 v[58:59], v[62:63], v[58:59]
	v_pk_mul_f32 v[52:53], v[56:57], v[52:53]
	v_mul_f32_e32 v68, 0x45800000, v66
	v_cndmask_b32_e32 v68, v66, v68, vcc
	v_mul_f32_e32 v66, 0xbfb8aa3b, v68
	v_pk_mul_f32 v[64:65], v[66:67], v[64:65] op_sel_hi:[0,1]
	v_pk_mul_f32 v[62:63], v[66:67], v[62:63] op_sel_hi:[0,1]
	v_pk_mul_f32 v[50:51], v[54:55], v[50:51]
	v_pk_mul_f32 v[56:57], v[66:67], v[56:57] op_sel_hi:[0,1]
	v_pk_mul_f32 v[54:55], v[66:67], v[54:55] op_sel_hi:[0,1]
	v_exp_f32_e32 v62, v62
	v_exp_f32_e32 v63, v63
	v_exp_f32_e32 v64, v64
	v_exp_f32_e32 v65, v65
	v_exp_f32_e32 v54, v54
	v_exp_f32_e32 v55, v55
	v_exp_f32_e32 v56, v56
	v_exp_f32_e32 v57, v57
	v_pk_add_f32 v[64:65], v[64:65], 1.0 op_sel_hi:[1,0]
	v_pk_add_f32 v[62:63], v[62:63], 1.0 op_sel_hi:[1,0]
	v_pk_add_f32 v[54:55], v[54:55], 1.0 op_sel_hi:[1,0]
	v_pk_add_f32 v[56:57], v[56:57], 1.0 op_sel_hi:[1,0]
	v_rcp_f32_e32 v62, v62
	v_rcp_f32_e32 v63, v63
	v_rcp_f32_e32 v64, v64
	v_rcp_f32_e32 v65, v65
	v_rcp_f32_e32 v54, v54
	v_rcp_f32_e32 v55, v55
	v_rcp_f32_e32 v56, v56
	v_rcp_f32_e32 v57, v57
	v_mul_f32_e32 v68, v68, v68
	v_pk_mul_f32 v[58:59], v[62:63], v[58:59]
	v_pk_mul_f32 v[60:61], v[64:65], v[60:61]
	v_pk_mul_f32 v[50:51], v[54:55], v[50:51]
	v_pk_mul_f32 v[52:53], v[56:57], v[52:53]
	v_pk_mul_f32 v[60:61], v[68:69], v[60:61] op_sel_hi:[0,1]
	v_pk_mul_f32 v[58:59], v[68:69], v[58:59] op_sel_hi:[0,1]
	v_pk_mul_f32 v[52:53], v[68:69], v[52:53] op_sel_hi:[0,1]
	v_pk_mul_f32 v[50:51], v[68:69], v[50:51] op_sel_hi:[0,1]
	v_cvt_pk_bf16_f32 v58, v58, v59
	v_cvt_pk_bf16_f32 v59, v60, v61
	v_cvt_pk_bf16_f32 v60, v50, v51
	v_cvt_pk_bf16_f32 v61, v52, v53
	v_mad_i64_i32 v[50:51], s[14:15], v67, s45, v[140:141]
	global_store_dwordx4 v[50:51], v[58:61], off
	v_fmamk_f32 v50, v148, 0x3a800000, v189
	v_cmp_gt_f32_e32 vcc, s27, v50
	v_mul_f32_e32 v52, 0x4b800000, v50
	v_add_u32_e32 v51, 0x90, v154
	v_cndmask_b32_e32 v50, v50, v52, vcc
	v_rsq_f32_e32 v50, v50
	v_pk_mul_f32 v[44:45], v[48:49], v[44:45]
	v_pk_mul_f32 v[42:43], v[46:47], v[42:43]
	v_pk_mul_f32 v[36:37], v[40:41], v[36:37]
	v_mul_f32_e32 v52, 0x45800000, v50
	v_cndmask_b32_e32 v52, v50, v52, vcc
	v_mul_f32_e32 v50, 0xbfb8aa3b, v52
	v_pk_mul_f32 v[48:49], v[50:51], v[48:49] op_sel_hi:[0,1]
	v_pk_mul_f32 v[46:47], v[50:51], v[46:47] op_sel_hi:[0,1]
	v_pk_mul_f32 v[34:35], v[38:39], v[34:35]
	v_pk_mul_f32 v[40:41], v[50:51], v[40:41] op_sel_hi:[0,1]
	v_pk_mul_f32 v[38:39], v[50:51], v[38:39] op_sel_hi:[0,1]
	v_exp_f32_e32 v46, v46
; __device__ __forceinline__ unsigned cvtpk(float lo, float hi) { f32x2_t v = {lo, hi}; bf16x2_t b = __builtin_convertvector(v, bf16x2_t); return __builtin_bit_cast(unsigned, b); }
;     __device__ __forceinline__ void prefetch(const Unit& u, int wr, int fr, float (&pre)[8]) const {
;         const int row0 = u.pm * 256 + wr * 64 + fr;
; #pragma unroll
;         for (int i = 0; i < 8; ++i) pre[i] = RS[row0 + (i >> 2) * 128 + (i & 3) * 16];
;     __device__ __forceinline__ void operator()(const f32x4 (&acc)[2][2][4][2], const Unit& u, int wr, int wc, int fr, int fq, const float (&pre)[8]) const {
;     ...
;             for (int m = 0; m < 4; ++m) { bf16_t* rowp = O + (size_t)(row0 + ai * 128 + m * 16) * ldc + col0; const float r = rsqrtf(pre[ai * 4 + m] * (1.f / 1024.f) + 1e-6f);
;                 const float k1 = r * -1.4426950408889634f, rr = r * r; u32x4 w;
; #pragma unroll
;                 for (int n = 0; n < 2; ++n) { const f32x4 g = acc[ai][0][m][n], uu = acc[ai][1][m][n]; const f32x4 t = g * uu, x = g * k1; f32x4 d;
;                     d[0] = __builtin_amdgcn_exp2f(x[0]); d[1] = __builtin_amdgcn_exp2f(x[1]); d[2] = __builtin_amdgcn_exp2f(x[2]); d[3] = __builtin_amdgcn_exp2f(x[3]);
;                     d = d + 1.0f;
;                     d[0] = __builtin_amdgcn_rcpf(d[0]); d[1] = __builtin_amdgcn_rcpf(d[1]); d[2] = __builtin_amdgcn_rcpf(d[2]); d[3] = __builtin_amdgcn_rcpf(d[3]);
;                     const f32x4 o = (t * d) * rr;
;                     if (n == 0) { w.x = cvtpk(o[0], o[1]); w.y = cvtpk(o[2], o[3]); } else { w.z = cvtpk(o[0], o[1]); w.w = cvtpk(o[2], o[3]); } }
;                 *(u32x4*)rowp = w; }
	v_exp_f32_e32 v47, v47
	v_exp_f32_e32 v48, v48
	v_exp_f32_e32 v49, v49
	v_exp_f32_e32 v38, v38
	v_exp_f32_e32 v39, v39
	v_exp_f32_e32 v40, v40
	v_exp_f32_e32 v41, v41
	v_pk_add_f32 v[48:49], v[48:49], 1.0 op_sel_hi:[1,0]
	v_pk_add_f32 v[46:47], v[46:47], 1.0 op_sel_hi:[1,0]
	v_pk_add_f32 v[38:39], v[38:39], 1.0 op_sel_hi:[1,0]
	v_pk_add_f32 v[40:41], v[40:41], 1.0 op_sel_hi:[1,0]
	v_rcp_f32_e32 v46, v46
	v_rcp_f32_e32 v47, v47
	v_rcp_f32_e32 v48, v48
	v_rcp_f32_e32 v49, v49
	v_rcp_f32_e32 v38, v38
	v_rcp_f32_e32 v39, v39
	v_rcp_f32_e32 v40, v40
	v_rcp_f32_e32 v41, v41
	v_mul_f32_e32 v52, v52, v52
	v_pk_mul_f32 v[42:43], v[46:47], v[42:43]
	v_pk_mul_f32 v[44:45], v[48:49], v[44:45]
	v_pk_mul_f32 v[34:35], v[38:39], v[34:35]
	v_pk_mul_f32 v[36:37], v[40:41], v[36:37]
	v_pk_mul_f32 v[44:45], v[52:53], v[44:45] op_sel_hi:[0,1]
	v_pk_mul_f32 v[42:43], v[52:53], v[42:43] op_sel_hi:[0,1]
	v_pk_mul_f32 v[36:37], v[52:53], v[36:37] op_sel_hi:[0,1]
	v_pk_mul_f32 v[34:35], v[52:53], v[34:35] op_sel_hi:[0,1]
	v_cvt_pk_bf16_f32 v42, v42, v43
	v_cvt_pk_bf16_f32 v43, v44, v45
	v_cvt_pk_bf16_f32 v44, v34, v35
	v_cvt_pk_bf16_f32 v45, v36, v37
	v_mad_i64_i32 v[34:35], s[14:15], v51, s45, v[140:141]
	global_store_dwordx4 v[34:35], v[42:45], off
	v_fmamk_f32 v34, v147, 0x3a800000, v189
	v_cmp_gt_f32_e32 vcc, s27, v34
	v_mul_f32_e32 v36, 0x4b800000, v34
	v_add_u32_e32 v35, 0xa0, v154
	v_cndmask_b32_e32 v34, v34, v36, vcc
	v_rsq_f32_e32 v34, v34
	v_pk_mul_f32 v[28:29], v[32:33], v[28:29]
	v_pk_mul_f32 v[26:27], v[30:31], v[26:27]
	v_pk_mul_f32 v[20:21], v[24:25], v[20:21]
	v_mul_f32_e32 v36, 0x45800000, v34
	v_cndmask_b32_e32 v36, v34, v36, vcc
	v_mul_f32_e32 v34, 0xbfb8aa3b, v36
	v_pk_mul_f32 v[32:33], v[34:35], v[32:33] op_sel_hi:[0,1]
	v_pk_mul_f32 v[30:31], v[34:35], v[30:31] op_sel_hi:[0,1]
	v_pk_mul_f32 v[18:19], v[22:23], v[18:19]
	v_pk_mul_f32 v[24:25], v[34:35], v[24:25] op_sel_hi:[0,1]
	v_pk_mul_f32 v[22:23], v[34:35], v[22:23] op_sel_hi:[0,1]
	v_exp_f32_e32 v30, v30
	v_exp_f32_e32 v31, v31
	v_exp_f32_e32 v32, v32
	v_exp_f32_e32 v33, v33
	v_exp_f32_e32 v22, v22
	v_exp_f32_e32 v23, v23
	v_exp_f32_e32 v24, v24
	v_exp_f32_e32 v25, v25
	v_pk_add_f32 v[32:33], v[32:33], 1.0 op_sel_hi:[1,0]
	v_pk_add_f32 v[30:31], v[30:31], 1.0 op_sel_hi:[1,0]
	v_pk_add_f32 v[22:23], v[22:23], 1.0 op_sel_hi:[1,0]
	v_pk_add_f32 v[24:25], v[24:25], 1.0 op_sel_hi:[1,0]
	v_rcp_f32_e32 v30, v30
	v_rcp_f32_e32 v31, v31
	v_rcp_f32_e32 v32, v32
	v_rcp_f32_e32 v33, v33
	v_rcp_f32_e32 v22, v22
	v_rcp_f32_e32 v23, v23
	v_rcp_f32_e32 v24, v24
	v_rcp_f32_e32 v25, v25
	v_mul_f32_e32 v36, v36, v36
	v_pk_mul_f32 v[26:27], v[30:31], v[26:27]
	v_pk_mul_f32 v[28:29], v[32:33], v[28:29]
	v_pk_mul_f32 v[18:19], v[22:23], v[18:19]
	v_pk_mul_f32 v[20:21], v[24:25], v[20:21]
	v_pk_mul_f32 v[28:29], v[36:37], v[28:29] op_sel_hi:[0,1]
	v_pk_mul_f32 v[26:27], v[36:37], v[26:27] op_sel_hi:[0,1]
	v_pk_mul_f32 v[20:21], v[36:37], v[20:21] op_sel_hi:[0,1]
	v_pk_mul_f32 v[18:19], v[36:37], v[18:19] op_sel_hi:[0,1]
	v_cvt_pk_bf16_f32 v26, v26, v27
	v_cvt_pk_bf16_f32 v27, v28, v29
	v_cvt_pk_bf16_f32 v28, v18, v19
	v_cvt_pk_bf16_f32 v29, v20, v21
	v_mad_i64_i32 v[18:19], s[14:15], v35, s45, v[140:141]
	global_store_dwordx4 v[18:19], v[26:29], off
	v_fmamk_f32 v18, v144, 0x3a800000, v189
	v_cmp_gt_f32_e32 vcc, s27, v18
	v_mul_f32_e32 v19, 0x4b800000, v18
	v_pk_mul_f32 v[12:13], v[16:17], v[12:13]
	v_cndmask_b32_e32 v18, v18, v19, vcc
	v_rsq_f32_e32 v18, v18
	v_pk_mul_f32 v[10:11], v[14:15], v[10:11]
	v_pk_mul_f32 v[2:3], v[6:7], v[2:3]
	v_pk_mul_f32 v[4:5], v[8:9], v[4:5]
	v_mul_f32_e32 v19, 0x45800000, v18
	v_cndmask_b32_e32 v19, v18, v19, vcc
	v_mul_f32_e32 v20, 0xbfb8aa3b, v19
	v_pk_mul_f32 v[16:17], v[20:21], v[16:17] op_sel_hi:[0,1]
	v_pk_mul_f32 v[14:15], v[20:21], v[14:15] op_sel_hi:[0,1]
	v_pk_mul_f32 v[6:7], v[20:21], v[6:7] op_sel_hi:[0,1]
	v_exp_f32_e32 v14, v14
	v_exp_f32_e32 v15, v15
	v_exp_f32_e32 v16, v16
	v_exp_f32_e32 v17, v17
	v_pk_mul_f32 v[8:9], v[20:21], v[8:9] op_sel_hi:[0,1]
	v_exp_f32_e32 v6, v6
	v_exp_f32_e32 v7, v7
	v_exp_f32_e32 v8, v8
	v_exp_f32_e32 v9, v9
	v_pk_add_f32 v[16:17], v[16:17], 1.0 op_sel_hi:[1,0]
	v_pk_add_f32 v[14:15], v[14:15], 1.0 op_sel_hi:[1,0]
	v_pk_add_f32 v[6:7], v[6:7], 1.0 op_sel_hi:[1,0]
	v_rcp_f32_e32 v14, v14
	v_rcp_f32_e32 v15, v15
	v_rcp_f32_e32 v16, v16
	v_rcp_f32_e32 v17, v17
	v_pk_add_f32 v[8:9], v[8:9], 1.0 op_sel_hi:[1,0]
	v_rcp_f32_e32 v6, v6
	v_rcp_f32_e32 v7, v7
	v_rcp_f32_e32 v8, v8
	v_rcp_f32_e32 v9, v9
	v_mul_f32_e32 v18, v19, v19
	v_pk_mul_f32 v[10:11], v[14:15], v[10:11]
	v_pk_mul_f32 v[12:13], v[16:17], v[12:13]
	v_pk_mul_f32 v[2:3], v[6:7], v[2:3]
	v_pk_mul_f32 v[12:13], v[18:19], v[12:13] op_sel_hi:[0,1]
	v_pk_mul_f32 v[10:11], v[18:19], v[10:11] op_sel_hi:[0,1]
	v_pk_mul_f32 v[4:5], v[8:9], v[4:5]
	v_pk_mul_f32 v[2:3], v[18:19], v[2:3] op_sel_hi:[0,1]
	v_cvt_pk_bf16_f32 v10, v10, v11
	v_cvt_pk_bf16_f32 v11, v12, v13
	v_pk_mul_f32 v[4:5], v[18:19], v[4:5] op_sel_hi:[0,1]
	v_cvt_pk_bf16_f32 v12, v2, v3
	v_add_u32_e32 v2, 0xb0, v154
	v_cvt_pk_bf16_f32 v13, v4, v5
	v_mad_i64_i32 v[2:3], s[14:15], v2, s45, v[140:141]
	s_mov_b64 s[16:17], -1
	s_and_b64 vcc, exec, s[36:37]
	global_store_dwordx4 v[2:3], v[10:13], off
	s_cbranch_vccnz .LBB0_172
	v_lshl_add_u32 v2, s82, 8, v142
	v_ashrrev_i32_e32 v3, 31, v2
	v_lshl_add_u64 v[2:3], v[2:3], 2, s[50:51]
	global_load_dword v153, v[2:3], off
	global_load_dword v152, v[2:3], off offset:64
	global_load_dword v151, v[2:3], off offset:128
	global_load_dword v150, v[2:3], off offset:192
	global_load_dword v149, v[2:3], off offset:512
	global_load_dword v148, v[2:3], off offset:576
	global_load_dword v147, v[2:3], off offset:640
	global_load_dword v144, v[2:3], off offset:704
	s_andn2_b64 vcc, exec, s[54:55]
	s_cbranch_vccnz .LBB0_171
	s_barrier
	s_branch .LBB0_171

; __device__ __forceinline__ unsigned cvtpk(float lo, float hi) { f32x2_t v = {lo, hi}; bf16x2_t b = __builtin_convertvector(v, bf16x2_t); return __builtin_bit_cast(unsigned, b); }
;     __device__ __forceinline__ void operator()(const f32x4 (&acc)[2][2][4][2], const Unit& u, int wr, int wc, int fr, int fq, const float (&pre)[8]) const {
;         const int row0 = u.pm * 256 + wr * 64 + fr, col0 = u.pn * 256 + wc * 32 + 8 * fq;
; #pragma unroll
;         for (int ai = 0; ai < 2; ++ai)
; #pragma unroll
;             for (int m = 0; m < 4; ++m) { bf16_t* rowp = O + (size_t)(row0 + ai * 128 + m * 16) * ldc + col0; const float r = RS ? rsqrtf(pre[ai * 4 + m] * (1.f / 1024.f) + 1e-6f) : 1.f;
; #pragma unroll
;                 for (int bj = 0; bj < 2; ++bj) { const f32x4 v0 = acc[ai][bj][m][0] * r, v1 = acc[ai][bj][m][1] * r; u32x4 w; w.x = cvtpk(v0[0], v0[1]); w.y = cvtpk(v0[2], v0[3]); w.z = cvtpk(v1[0], v1[1]); w.w = cvtpk(v1[2], v1[3]);
;                     *(u32x4*)(rowp + bj * 128) = w; } }
.LBB0_227:
	v_lshl_add_u32 v153, s93, 8, v145
	v_ashrrev_i32_e32 v141, 31, v153
	v_mul_lo_u32 v160, s68, v141
	v_mul_lo_u32 v141, s69, v153
	v_mad_u64_u32 v[156:157], s[14:15], s68, v153, 0
	s_waitcnt vmcnt(8)
	v_fmamk_f32 v140, v140, 0x3a800000, v189
	v_add3_u32 v157, v157, v160, v141
	v_mul_f32_e32 v141, 0x4b800000, v140
	v_cmp_gt_f32_e32 vcc, s27, v140
	v_lshl_or_b32 v154, s91, 8, v151
	v_ashrrev_i32_e32 v155, 31, v154
	v_cndmask_b32_e32 v140, v140, v141, vcc
	v_rsq_f32_e32 v158, v140
	v_lshl_add_u64 v[156:157], v[156:157], 1, s[62:63]
	v_lshlrev_b64 v[140:141], 1, v[154:155]
	v_lshl_add_u64 v[154:155], v[156:157], 0, v[140:141]
	v_mul_f32_e32 v156, 0x45800000, v158
	v_cndmask_b32_e32 v156, v158, v156, vcc
	v_cndmask_b32_e64 v156, v156, 1.0, s[70:71]
	v_pk_mul_f32 v[128:129], v[156:157], v[128:129] op_sel_hi:[0,1]
	v_pk_mul_f32 v[126:127], v[156:157], v[126:127] op_sel_hi:[0,1]
	v_pk_mul_f32 v[158:159], v[156:157], v[124:125] op_sel_hi:[0,1]
	v_pk_mul_f32 v[124:125], v[156:157], v[122:123] op_sel_hi:[0,1]
	v_cvt_pk_bf16_f32 v122, v126, v127
	v_cvt_pk_bf16_f32 v123, v128, v129
	v_cvt_pk_bf16_f32 v124, v124, v125
	v_cvt_pk_bf16_f32 v125, v158, v159
	global_store_dwordx4 v[154:155], v[122:125], off
	v_pk_mul_f32 v[120:121], v[156:157], v[120:121] op_sel_hi:[0,1]
	v_pk_mul_f32 v[118:119], v[156:157], v[118:119] op_sel_hi:[0,1]
	v_pk_mul_f32 v[122:123], v[156:157], v[116:117] op_sel_hi:[0,1]
	v_pk_mul_f32 v[116:117], v[156:157], v[114:115] op_sel_hi:[0,1]
	v_cvt_pk_bf16_f32 v114, v118, v119
	v_cvt_pk_bf16_f32 v115, v120, v121
	v_cvt_pk_bf16_f32 v116, v116, v117
	v_cvt_pk_bf16_f32 v117, v122, v123
	global_store_dwordx4 v[154:155], v[114:117], off offset:256
	s_mov_b64 s[30:31], -1
	s_nop 0
	v_fmamk_f32 v117, v150, 0x3a800000, v189
	v_mul_f32_e32 v118, 0x4b800000, v117
	v_cmp_gt_f32_e32 vcc, s27, v117
	v_or_b32_e32 v114, 16, v153
	v_mul_lo_u32 v116, s69, v114
	v_cndmask_b32_e32 v117, v117, v118, vcc
	v_rsq_f32_e32 v117, v117
	v_mad_u64_u32 v[114:115], s[14:15], s68, v114, 0
	v_add3_u32 v115, v115, v160, v116
	v_mul_f32_e32 v116, 0x45800000, v117
	v_cndmask_b32_e32 v116, v117, v116, vcc
	v_cndmask_b32_e64 v116, v116, 1.0, s[70:71]
	v_lshl_add_u64 v[114:115], v[114:115], 1, s[62:63]
	v_pk_mul_f32 v[112:113], v[116:117], v[112:113] op_sel_hi:[0,1]
	v_pk_mul_f32 v[110:111], v[116:117], v[110:111] op_sel_hi:[0,1]
	v_pk_mul_f32 v[118:119], v[116:117], v[108:109] op_sel_hi:[0,1]
	v_pk_mul_f32 v[108:109], v[116:117], v[106:107] op_sel_hi:[0,1]
	v_lshl_add_u64 v[114:115], v[114:115], 0, v[140:141]
	v_cvt_pk_bf16_f32 v106, v110, v111
	v_cvt_pk_bf16_f32 v107, v112, v113
	v_cvt_pk_bf16_f32 v108, v108, v109
	v_cvt_pk_bf16_f32 v109, v118, v119
	global_store_dwordx4 v[114:115], v[106:109], off
	v_pk_mul_f32 v[104:105], v[116:117], v[104:105] op_sel_hi:[0,1]
	v_pk_mul_f32 v[102:103], v[116:117], v[102:103] op_sel_hi:[0,1]
	v_pk_mul_f32 v[106:107], v[116:117], v[100:101] op_sel_hi:[0,1]
	v_pk_mul_f32 v[100:101], v[116:117], v[98:99] op_sel_hi:[0,1]
	v_cvt_pk_bf16_f32 v98, v102, v103
	v_cvt_pk_bf16_f32 v99, v104, v105
	v_cvt_pk_bf16_f32 v100, v100, v101
	v_cvt_pk_bf16_f32 v101, v106, v107
	global_store_dwordx4 v[114:115], v[98:101], off offset:256
	s_nop 1
	v_fmamk_f32 v101, v149, 0x3a800000, v189
	v_mul_f32_e32 v102, 0x4b800000, v101
	v_cmp_gt_f32_e32 vcc, s27, v101
	v_or_b32_e32 v98, 32, v153
	v_mul_lo_u32 v100, s69, v98
	v_cndmask_b32_e32 v101, v101, v102, vcc
	v_rsq_f32_e32 v101, v101
	v_mad_u64_u32 v[98:99], s[14:15], s68, v98, 0
	v_add3_u32 v99, v99, v160, v100
	v_mul_f32_e32 v100, 0x45800000, v101
	v_cndmask_b32_e32 v100, v101, v100, vcc
	v_cndmask_b32_e64 v100, v100, 1.0, s[70:71]
	v_lshl_add_u64 v[98:99], v[98:99], 1, s[62:63]
	v_pk_mul_f32 v[96:97], v[100:101], v[96:97] op_sel_hi:[0,1]
	v_pk_mul_f32 v[94:95], v[100:101], v[94:95] op_sel_hi:[0,1]
	v_pk_mul_f32 v[102:103], v[100:101], v[92:93] op_sel_hi:[0,1]
	v_pk_mul_f32 v[92:93], v[100:101], v[90:91] op_sel_hi:[0,1]
	v_lshl_add_u64 v[98:99], v[98:99], 0, v[140:141]
	v_cvt_pk_bf16_f32 v90, v94, v95
	v_cvt_pk_bf16_f32 v91, v96, v97
	v_cvt_pk_bf16_f32 v92, v92, v93
	v_cvt_pk_bf16_f32 v93, v102, v103
	global_store_dwordx4 v[98:99], v[90:93], off
	v_pk_mul_f32 v[88:89], v[100:101], v[88:89] op_sel_hi:[0,1]
	v_pk_mul_f32 v[86:87], v[100:101], v[86:87] op_sel_hi:[0,1]
	v_pk_mul_f32 v[90:91], v[100:101], v[84:85] op_sel_hi:[0,1]
	v_pk_mul_f32 v[84:85], v[100:101], v[82:83] op_sel_hi:[0,1]
	v_cvt_pk_bf16_f32 v82, v86, v87
	v_cvt_pk_bf16_f32 v83, v88, v89
	v_cvt_pk_bf16_f32 v84, v84, v85
	v_cvt_pk_bf16_f32 v85, v90, v91
	global_store_dwordx4 v[98:99], v[82:85], off offset:256
	s_nop 1
	v_fmamk_f32 v85, v148, 0x3a800000, v189
	v_mul_f32_e32 v86, 0x4b800000, v85
	v_cmp_gt_f32_e32 vcc, s27, v85
	v_or_b32_e32 v82, 48, v153
	v_mul_lo_u32 v84, s69, v82
	v_cndmask_b32_e32 v85, v85, v86, vcc
	v_rsq_f32_e32 v85, v85
	v_mad_u64_u32 v[82:83], s[14:15], s68, v82, 0
	v_add3_u32 v83, v83, v160, v84
	v_mul_f32_e32 v84, 0x45800000, v85
	v_cndmask_b32_e32 v84, v85, v84, vcc
	v_cndmask_b32_e64 v84, v84, 1.0, s[70:71]
	v_lshl_add_u64 v[82:83], v[82:83], 1, s[62:63]
	v_pk_mul_f32 v[80:81], v[84:85], v[80:81] op_sel_hi:[0,1]
	v_pk_mul_f32 v[78:79], v[84:85], v[78:79] op_sel_hi:[0,1]
	v_pk_mul_f32 v[86:87], v[84:85], v[76:77] op_sel_hi:[0,1]
	v_pk_mul_f32 v[76:77], v[84:85], v[74:75] op_sel_hi:[0,1]
	v_lshl_add_u64 v[82:83], v[82:83], 0, v[140:141]
	v_cvt_pk_bf16_f32 v74, v78, v79
	v_cvt_pk_bf16_f32 v75, v80, v81
	v_cvt_pk_bf16_f32 v76, v76, v77
	v_cvt_pk_bf16_f32 v77, v86, v87
	v_pk_mul_f32 v[70:71], v[84:85], v[70:71] op_sel_hi:[0,1]
	global_store_dwordx4 v[82:83], v[74:77], off
	v_pk_mul_f32 v[72:73], v[84:85], v[72:73] op_sel_hi:[0,1]
	s_nop 0
	v_pk_mul_f32 v[74:75], v[84:85], v[68:69] op_sel_hi:[0,1]
	v_pk_mul_f32 v[68:69], v[84:85], v[66:67] op_sel_hi:[0,1]
	v_cvt_pk_bf16_f32 v66, v70, v71
	s_waitcnt vmcnt(0)
; __device__ __forceinline__ unsigned cvtpk(float lo, float hi) { f32x2_t v = {lo, hi}; bf16x2_t b = __builtin_convertvector(v, bf16x2_t); return __builtin_bit_cast(unsigned, b); }
;     __device__ __forceinline__ void prefetch(const Unit& u, int wr, int fr, float (&pre)[8]) const {
;         const int row0 = u.pm * 256 + wr * 64 + fr;
; #pragma unroll
;         for (int i = 0; i < 8; ++i) pre[i] = RS ? RS[row0 + (i >> 2) * 128 + (i & 3) * 16] : 0.f;
;     __device__ __forceinline__ void operator()(const f32x4 (&acc)[2][2][4][2], const Unit& u, int wr, int wc, int fr, int fq, const float (&pre)[8]) const {
;         const int row0 = u.pm * 256 + wr * 64 + fr, col0 = u.pn * 256 + wc * 32 + 8 * fq;
; #pragma unroll
;         for (int ai = 0; ai < 2; ++ai)
; #pragma unroll
;             for (int m = 0; m < 4; ++m) { bf16_t* rowp = O + (size_t)(row0 + ai * 128 + m * 16) * ldc + col0; const float r = RS ? rsqrtf(pre[ai * 4 + m] * (1.f / 1024.f) + 1e-6f) : 1.f;
; #pragma unroll
;                 for (int bj = 0; bj < 2; ++bj) { const f32x4 v0 = acc[ai][bj][m][0] * r, v1 = acc[ai][bj][m][1] * r; u32x4 w; w.x = cvtpk(v0[0], v0[1]); w.y = cvtpk(v0[2], v0[3]); w.z = cvtpk(v1[0], v1[1]); w.w = cvtpk(v1[2], v1[3]);
;                     *(u32x4*)(rowp + bj * 128) = w; } }
	v_fmamk_f32 v70, v146, 0x3a800000, v189
	v_mul_f32_e32 v71, 0x4b800000, v70
	v_cmp_gt_f32_e32 vcc, s27, v70
	v_cvt_pk_bf16_f32 v67, v72, v73
	v_cvt_pk_bf16_f32 v68, v68, v69
	v_cndmask_b32_e32 v70, v70, v71, vcc
	v_cvt_pk_bf16_f32 v69, v74, v75
	v_rsq_f32_e32 v70, v70
	global_store_dwordx4 v[82:83], v[66:69], off offset:256
	s_nop 1
	v_add_u32_e32 v66, 0x80, v153
	v_ashrrev_i32_e32 v67, 31, v66
	v_mul_lo_u32 v68, s68, v67
	v_mul_lo_u32 v69, s69, v66
	v_mad_u64_u32 v[66:67], s[14:15], s68, v66, 0
	v_add3_u32 v67, v67, v68, v69
	v_mul_f32_e32 v68, 0x45800000, v70
	v_cndmask_b32_e32 v68, v70, v68, vcc
	v_cndmask_b32_e64 v68, v68, 1.0, s[70:71]
	v_lshl_add_u64 v[66:67], v[66:67], 1, s[62:63]
	v_pk_mul_f32 v[64:65], v[68:69], v[64:65] op_sel_hi:[0,1]
	v_pk_mul_f32 v[62:63], v[68:69], v[62:63] op_sel_hi:[0,1]
	v_pk_mul_f32 v[70:71], v[68:69], v[60:61] op_sel_hi:[0,1]
	v_pk_mul_f32 v[60:61], v[68:69], v[58:59] op_sel_hi:[0,1]
	v_lshl_add_u64 v[66:67], v[66:67], 0, v[140:141]
	v_cvt_pk_bf16_f32 v58, v62, v63
	v_cvt_pk_bf16_f32 v59, v64, v65
	v_cvt_pk_bf16_f32 v60, v60, v61
	v_cvt_pk_bf16_f32 v61, v70, v71
	v_pk_mul_f32 v[54:55], v[68:69], v[54:55] op_sel_hi:[0,1]
	global_store_dwordx4 v[66:67], v[58:61], off
	v_pk_mul_f32 v[56:57], v[68:69], v[56:57] op_sel_hi:[0,1]
	s_nop 0
	v_pk_mul_f32 v[58:59], v[68:69], v[52:53] op_sel_hi:[0,1]
	v_pk_mul_f32 v[52:53], v[68:69], v[50:51] op_sel_hi:[0,1]
	v_cvt_pk_bf16_f32 v50, v54, v55
	v_fmamk_f32 v54, v144, 0x3a800000, v189
	v_mul_f32_e32 v55, 0x4b800000, v54
	v_cmp_gt_f32_e32 vcc, s27, v54
	v_cvt_pk_bf16_f32 v51, v56, v57
	v_cvt_pk_bf16_f32 v52, v52, v53
	v_cndmask_b32_e32 v54, v54, v55, vcc
	v_cvt_pk_bf16_f32 v53, v58, v59
	v_rsq_f32_e32 v54, v54
	global_store_dwordx4 v[66:67], v[50:53], off offset:256
	s_nop 1
	v_add_u32_e32 v50, 0x90, v153
	v_ashrrev_i32_e32 v51, 31, v50
	v_mul_lo_u32 v52, s68, v51
	v_mul_lo_u32 v53, s69, v50
	v_mad_u64_u32 v[50:51], s[14:15], s68, v50, 0
	v_add3_u32 v51, v51, v52, v53
	v_mul_f32_e32 v52, 0x45800000, v54
	v_cndmask_b32_e32 v52, v54, v52, vcc
	v_cndmask_b32_e64 v52, v52, 1.0, s[70:71]
	v_lshl_add_u64 v[50:51], v[50:51], 1, s[62:63]
	v_pk_mul_f32 v[48:49], v[52:53], v[48:49] op_sel_hi:[0,1]
	v_pk_mul_f32 v[46:47], v[52:53], v[46:47] op_sel_hi:[0,1]
	v_pk_mul_f32 v[54:55], v[52:53], v[44:45] op_sel_hi:[0,1]
	v_pk_mul_f32 v[44:45], v[52:53], v[42:43] op_sel_hi:[0,1]
	v_lshl_add_u64 v[50:51], v[50:51], 0, v[140:141]
	v_cvt_pk_bf16_f32 v42, v46, v47
	v_cvt_pk_bf16_f32 v43, v48, v49
	v_cvt_pk_bf16_f32 v44, v44, v45
	v_cvt_pk_bf16_f32 v45, v54, v55
	v_pk_mul_f32 v[38:39], v[52:53], v[38:39] op_sel_hi:[0,1]
	global_store_dwordx4 v[50:51], v[42:45], off
	v_pk_mul_f32 v[40:41], v[52:53], v[40:41] op_sel_hi:[0,1]
	s_nop 0
	v_pk_mul_f32 v[42:43], v[52:53], v[36:37] op_sel_hi:[0,1]
	v_pk_mul_f32 v[36:37], v[52:53], v[34:35] op_sel_hi:[0,1]
	v_cvt_pk_bf16_f32 v34, v38, v39
	v_fmamk_f32 v38, v143, 0x3a800000, v189
	v_mul_f32_e32 v39, 0x4b800000, v38
	v_cmp_gt_f32_e32 vcc, s27, v38
	v_cvt_pk_bf16_f32 v35, v40, v41
	v_cvt_pk_bf16_f32 v36, v36, v37
	v_cndmask_b32_e32 v38, v38, v39, vcc
	v_cvt_pk_bf16_f32 v37, v42, v43
	v_rsq_f32_e32 v38, v38
	global_store_dwordx4 v[50:51], v[34:37], off offset:256
	s_nop 1
	v_add_u32_e32 v34, 0xa0, v153
	v_ashrrev_i32_e32 v35, 31, v34
	v_mul_lo_u32 v36, s68, v35
	v_mul_lo_u32 v37, s69, v34
	v_mad_u64_u32 v[34:35], s[14:15], s68, v34, 0
	v_add3_u32 v35, v35, v36, v37
	v_mul_f32_e32 v36, 0x45800000, v38
	v_cndmask_b32_e32 v36, v38, v36, vcc
	v_cndmask_b32_e64 v36, v36, 1.0, s[70:71]
	v_lshl_add_u64 v[34:35], v[34:35], 1, s[62:63]
	v_pk_mul_f32 v[32:33], v[36:37], v[32:33] op_sel_hi:[0,1]
	v_pk_mul_f32 v[30:31], v[36:37], v[30:31] op_sel_hi:[0,1]
	v_pk_mul_f32 v[38:39], v[36:37], v[28:29] op_sel_hi:[0,1]
	v_pk_mul_f32 v[28:29], v[36:37], v[26:27] op_sel_hi:[0,1]
	v_lshl_add_u64 v[34:35], v[34:35], 0, v[140:141]
	v_cvt_pk_bf16_f32 v26, v30, v31
	v_cvt_pk_bf16_f32 v27, v32, v33
	v_cvt_pk_bf16_f32 v28, v28, v29
	v_cvt_pk_bf16_f32 v29, v38, v39
	v_pk_mul_f32 v[22:23], v[36:37], v[22:23] op_sel_hi:[0,1]
	global_store_dwordx4 v[34:35], v[26:29], off
	v_pk_mul_f32 v[24:25], v[36:37], v[24:25] op_sel_hi:[0,1]
	s_nop 0
	v_pk_mul_f32 v[26:27], v[36:37], v[20:21] op_sel_hi:[0,1]
	v_pk_mul_f32 v[20:21], v[36:37], v[18:19] op_sel_hi:[0,1]
	v_cvt_pk_bf16_f32 v18, v22, v23
	v_fmamk_f32 v22, v142, 0x3a800000, v189
	v_mul_f32_e32 v23, 0x4b800000, v22
	v_cmp_gt_f32_e32 vcc, s27, v22
	v_cvt_pk_bf16_f32 v19, v24, v25
	v_cvt_pk_bf16_f32 v20, v20, v21
	v_cndmask_b32_e32 v22, v22, v23, vcc
	v_rsq_f32_e32 v22, v22
	v_cvt_pk_bf16_f32 v21, v26, v27
	global_store_dwordx4 v[34:35], v[18:21], off offset:256
	s_nop 1
	v_add_u32_e32 v19, 0xb0, v153
	v_mul_f32_e32 v18, 0x45800000, v22
	v_ashrrev_i32_e32 v20, 31, v19
	v_cndmask_b32_e32 v18, v22, v18, vcc
	v_mul_lo_u32 v22, s68, v20
	v_mul_lo_u32 v23, s69, v19
	v_mad_u64_u32 v[20:21], s[14:15], s68, v19, 0
	v_cndmask_b32_e64 v18, v18, 1.0, s[70:71]
	v_add3_u32 v21, v21, v22, v23
	v_lshl_add_u64 v[20:21], v[20:21], 1, s[62:63]
	v_pk_mul_f32 v[16:17], v[18:19], v[16:17] op_sel_hi:[0,1]
	v_pk_mul_f32 v[14:15], v[18:19], v[14:15] op_sel_hi:[0,1]
	v_pk_mul_f32 v[22:23], v[18:19], v[12:13] op_sel_hi:[0,1]
	v_pk_mul_f32 v[12:13], v[18:19], v[10:11] op_sel_hi:[0,1]
	v_lshl_add_u64 v[20:21], v[20:21], 0, v[140:141]
	v_cvt_pk_bf16_f32 v10, v14, v15
	v_cvt_pk_bf16_f32 v11, v16, v17
	v_cvt_pk_bf16_f32 v12, v12, v13
	v_cvt_pk_bf16_f32 v13, v22, v23
	global_store_dwordx4 v[20:21], v[10:13], off
	v_pk_mul_f32 v[8:9], v[18:19], v[8:9] op_sel_hi:[0,1]
	v_pk_mul_f32 v[6:7], v[18:19], v[6:7] op_sel_hi:[0,1]
	v_pk_mul_f32 v[10:11], v[18:19], v[4:5] op_sel_hi:[0,1]
	v_pk_mul_f32 v[4:5], v[18:19], v[2:3] op_sel_hi:[0,1]
	v_cvt_pk_bf16_f32 v2, v6, v7
	v_cvt_pk_bf16_f32 v3, v8, v9
	v_cvt_pk_bf16_f32 v4, v4, v5
	v_cvt_pk_bf16_f32 v5, v10, v11
	s_and_b64 vcc, exec, s[38:39]
	global_store_dwordx4 v[20:21], v[2:5], off offset:256
	s_cbranch_vccnz .LBB0_212
	s_nop 0
	v_lshl_add_u32 v2, s95, 8, v145
	v_mov_b32_e32 v149, 0
	s_and_b64 vcc, exec, s[36:37]
	v_ashrrev_i32_e32 v3, 31, v2
	v_mov_b32_e32 v140, 0
	v_mov_b32_e32 v150, 0
	s_cbranch_vccnz .LBB0_230
	v_lshl_add_u64 v[4:5], v[2:3], 2, s[66:67]
	global_load_dword v140, v[4:5], off
	global_load_dword v150, v[4:5], off offset:64
